# SSD part 1 dt projection: H row chunks prefetched 4 deep (4 register sets) instead of 1 chunk ahead, on top of the pipelined mixer-B loop
# speedup vs baseline: 1.0006x; 1.0006x over previous
; #define LAS __attribute__((address_space(3)))
; #define MFMA16(a, b, c) __builtin_amdgcn_mfma_f32_16x16x32_bf16((a), (b), (c), 0, 0, 0)
; DI void ssd_part1_unit(int u, const bf16* PROJ, float* DT, const bf16* H, const bf16* wdtb_l, const float* dt_bias_l, const float* cw, const float* cb, const float* a_log_l, float* STATES, float* TOT,
;                        LAS unsigned char* ldsu, int tid, int wave, int lane) {
;     ...
;         LAS char* hst = lds + 2 * IMG_BYTES + wave * (16 * IMG_PITCH);
;         for (int i = tid; i < 1024; i += 512) { const int row = i >> 7, ch = i & 127; *(LAS u32x4*)(wl + row * 2064 + ch * 16) = *(const u32x4*)(wdtb_l + (size_t)row * 1024 + ch * 8); }
;         __syncthreads();
;         f32x4 dacc = {0.f, 0.f, 0.f, 0.f};
;         const bf16* hrow = H + (size_t)(b * T + t0 + 16 * wave) * 1024;
;         u32x4 hv[4];
; #pragma unroll
;         for (int it = 0; it < 4; ++it) { const int n = lane + 64 * it; hv[it] = __builtin_nontemporal_load((const u32x4*)(hrow + (size_t)(n >> 4) * 1024 + (n & 15) * 8)); }
;         for (int ck = 0; ck < 8; ++ck) {
; #pragma unroll
;             for (int it = 0; it < 4; ++it) { const int n = lane + 64 * it; *(LAS u32x4*)(hst + (n >> 4) * IMG_PITCH + (n & 15) * 16) = hv[it]; }
;             if (ck + 1 < 8) {
; #pragma unroll
;                 for (int it = 0; it < 4; ++it) { const int n = lane + 64 * it; hv[it] = __builtin_nontemporal_load((const u32x4*)(hrow + (size_t)(n >> 4) * 1024 + (ck + 1) * 128 + (n & 15) * 8)); } }
; #pragma unroll
;             for (int ks = 0; ks < 4; ++ks) {
;                 const bf16x8 af = *(const LAS bf16x8*)(hst + r * IMG_PITCH + 64 * ks + 16 * g);
;                 bf16x8 bfw = {0, 0, 0, 0, 0, 0, 0, 0};
;                 if (r < 8) bfw = *(const LAS bf16x8*)(wl + r * 2064 + (ck * 128 + 32 * ks + 8 * g) * 2);
;                 dacc = MFMA16(af, bfw, dacc);
;             }
;             asm volatile("" ::: "memory");
;         }
.LBB0_269:
	s_or_b64 exec, exec, s[0:1]
	s_ashr_i32 s62, s31, 5
	s_bfe_u32 s34, s31, 0x40001
	s_lshl_b32 s0, s62, 11
	s_lshl_b32 s57, s34, 7
	s_add_i32 s0, s0, s30
	s_add_i32 s0, s0, s57
	s_ashr_i32 s1, s0, 31
	s_lshl_b64 s[60:61], s[0:1], 11
	v_lshl_add_u64 v[34:35], v[104:105], 0, s[60:61]
	v_mov_b32_e32 v115, v189
	v_lshl_add_u64 v[36:37], v[34:35], 0, v[114:115]
	s_waitcnt lgkmcnt(0)
	s_barrier
	v_mov_b32_e32 v117, v189
	v_mov_b32_e32 v119, v189
	v_lshl_add_u64 v[86:87], v[34:35], 0, v[188:189]
	v_lshl_add_u64 v[88:89], v[34:35], 0, v[116:117]
	v_lshl_add_u64 v[90:91], v[34:35], 0, v[118:119]
	global_load_dwordx4 v[4:7], v[36:37], off nt
	global_load_dwordx4 v[8:11], v[86:87], off nt
	global_load_dwordx4 v[12:15], v[88:89], off nt
	global_load_dwordx4 v[16:19], v[90:91], off nt
	global_load_dwordx4 v[38:41], v[36:37], off offset:256 nt
	global_load_dwordx4 v[42:45], v[86:87], off offset:256 nt
	global_load_dwordx4 v[46:49], v[88:89], off offset:256 nt
	global_load_dwordx4 v[50:53], v[90:91], off offset:256 nt
	global_load_dwordx4 v[54:57], v[36:37], off offset:512 nt
	global_load_dwordx4 v[58:61], v[86:87], off offset:512 nt
	global_load_dwordx4 v[62:65], v[88:89], off offset:512 nt
	global_load_dwordx4 v[66:69], v[90:91], off offset:512 nt
	global_load_dwordx4 v[70:73], v[36:37], off offset:768 nt
	global_load_dwordx4 v[74:77], v[86:87], off offset:768 nt
	global_load_dwordx4 v[78:81], v[88:89], off offset:768 nt
	global_load_dwordx4 v[82:85], v[90:91], off offset:768 nt
	v_mov_b32_e32 v20, 0
	v_mov_b32_e32 v21, 0
	v_mov_b32_e32 v22, 0
	v_mov_b32_e32 v23, 0
	v_mov_b32_e32 v92, 0
	v_mov_b32_e32 v93, 0
	v_mov_b32_e32 v94, 0
	v_mov_b32_e32 v95, 0
	v_mov_b32_e32 v96, 0
	v_mov_b32_e32 v97, 0
	v_mov_b32_e32 v98, 0
	v_mov_b32_e32 v99, 0
	s_waitcnt vmcnt(12)
	ds_write_b128 v244, v[4:7]
	ds_write_b128 v244, v[8:11] offset:1088
	ds_write_b128 v244, v[12:15] offset:2176
	ds_write_b128 v244, v[16:19] offset:3264
	global_load_dwordx4 v[4:7], v[36:37], off offset:1024 nt
	global_load_dwordx4 v[8:11], v[86:87], off offset:1024 nt
	global_load_dwordx4 v[12:15], v[88:89], off offset:1024 nt
	global_load_dwordx4 v[16:19], v[90:91], off offset:1024 nt
	ds_read_b128 v[24:27], v245
	ds_read_b128 v[28:31], v245 offset:64
	s_and_saveexec_b64 s[60:61], s[38:39]
	ds_read_b128 v[92:95], v246
	ds_read_b128 v[96:99], v246 offset:64
	s_or_b64 exec, exec, s[60:61]
	s_waitcnt lgkmcnt(0)
	v_mfma_f32_16x16x32_bf16 v[20:23], v[24:27], v[92:95], v[20:23]
	v_mfma_f32_16x16x32_bf16 v[20:23], v[28:31], v[96:99], v[20:23]
	ds_read_b128 v[24:27], v245 offset:128
	ds_read_b128 v[28:31], v245 offset:192
	s_and_saveexec_b64 s[60:61], s[38:39]
	ds_read_b128 v[92:95], v246 offset:128
	ds_read_b128 v[96:99], v246 offset:192
	s_or_b64 exec, exec, s[60:61]
	s_waitcnt lgkmcnt(0)
	v_mfma_f32_16x16x32_bf16 v[20:23], v[24:27], v[92:95], v[20:23]
	v_mfma_f32_16x16x32_bf16 v[20:23], v[28:31], v[96:99], v[20:23]
	s_waitcnt vmcnt(12)
	ds_write_b128 v244, v[38:41]
	ds_write_b128 v244, v[42:45] offset:1088
	ds_write_b128 v244, v[46:49] offset:2176
	ds_write_b128 v244, v[50:53] offset:3264
	global_load_dwordx4 v[38:41], v[36:37], off offset:1280 nt
	global_load_dwordx4 v[42:45], v[86:87], off offset:1280 nt
	global_load_dwordx4 v[46:49], v[88:89], off offset:1280 nt
	global_load_dwordx4 v[50:53], v[90:91], off offset:1280 nt
	ds_read_b128 v[24:27], v245
	ds_read_b128 v[28:31], v245 offset:64
	s_and_saveexec_b64 s[60:61], s[38:39]
	ds_read_b128 v[92:95], v246 offset:256
	ds_read_b128 v[96:99], v246 offset:320
	s_or_b64 exec, exec, s[60:61]
	s_waitcnt lgkmcnt(0)
	v_mfma_f32_16x16x32_bf16 v[20:23], v[24:27], v[92:95], v[20:23]
	v_mfma_f32_16x16x32_bf16 v[20:23], v[28:31], v[96:99], v[20:23]
	ds_read_b128 v[24:27], v245 offset:128
	ds_read_b128 v[28:31], v245 offset:192
	s_and_saveexec_b64 s[60:61], s[38:39]
	ds_read_b128 v[92:95], v246 offset:384
	ds_read_b128 v[96:99], v246 offset:448
	s_or_b64 exec, exec, s[60:61]
	s_waitcnt lgkmcnt(0)
	v_mfma_f32_16x16x32_bf16 v[20:23], v[24:27], v[92:95], v[20:23]
	v_mfma_f32_16x16x32_bf16 v[20:23], v[28:31], v[96:99], v[20:23]
	s_waitcnt vmcnt(12)
	ds_write_b128 v244, v[54:57]
	ds_write_b128 v244, v[58:61] offset:1088
	ds_write_b128 v244, v[62:65] offset:2176
	ds_write_b128 v244, v[66:69] offset:3264
	global_load_dwordx4 v[54:57], v[36:37], off offset:1536 nt
	global_load_dwordx4 v[58:61], v[86:87], off offset:1536 nt
	global_load_dwordx4 v[62:65], v[88:89], off offset:1536 nt
	global_load_dwordx4 v[66:69], v[90:91], off offset:1536 nt
	ds_read_b128 v[24:27], v245
	ds_read_b128 v[28:31], v245 offset:64
	s_and_saveexec_b64 s[60:61], s[38:39]
	ds_read_b128 v[92:95], v246 offset:512
	ds_read_b128 v[96:99], v246 offset:576
	s_or_b64 exec, exec, s[60:61]
	s_waitcnt lgkmcnt(0)
	v_mfma_f32_16x16x32_bf16 v[20:23], v[24:27], v[92:95], v[20:23]
	v_mfma_f32_16x16x32_bf16 v[20:23], v[28:31], v[96:99], v[20:23]
	ds_read_b128 v[24:27], v245 offset:128
	ds_read_b128 v[28:31], v245 offset:192
	s_and_saveexec_b64 s[60:61], s[38:39]
	ds_read_b128 v[92:95], v246 offset:640
	ds_read_b128 v[96:99], v246 offset:704
	s_or_b64 exec, exec, s[60:61]
	s_waitcnt lgkmcnt(0)
	v_mfma_f32_16x16x32_bf16 v[20:23], v[24:27], v[92:95], v[20:23]
	v_mfma_f32_16x16x32_bf16 v[20:23], v[28:31], v[96:99], v[20:23]
	s_waitcnt vmcnt(12)
	ds_write_b128 v244, v[70:73]
	ds_write_b128 v244, v[74:77] offset:1088
	ds_write_b128 v244, v[78:81] offset:2176
	ds_write_b128 v244, v[82:85] offset:3264
	global_load_dwordx4 v[70:73], v[36:37], off offset:1792 nt
	global_load_dwordx4 v[74:77], v[86:87], off offset:1792 nt
	global_load_dwordx4 v[78:81], v[88:89], off offset:1792 nt
	global_load_dwordx4 v[82:85], v[90:91], off offset:1792 nt
	ds_read_b128 v[24:27], v245
	ds_read_b128 v[28:31], v245 offset:64
	s_and_saveexec_b64 s[60:61], s[38:39]
	ds_read_b128 v[92:95], v246 offset:768
	ds_read_b128 v[96:99], v246 offset:832
	s_or_b64 exec, exec, s[60:61]
	s_waitcnt lgkmcnt(0)
; #define LAS __attribute__((address_space(3)))
; #define MFMA16(a, b, c) __builtin_amdgcn_mfma_f32_16x16x32_bf16((a), (b), (c), 0, 0, 0)
; DI void ssd_part1_unit(int u, const bf16* PROJ, float* DT, const bf16* H, const bf16* wdtb_l, const float* dt_bias_l, const float* cw, const float* cb, const float* a_log_l, float* STATES, float* TOT,
;                        LAS unsigned char* ldsu, int tid, int wave, int lane) {
;     ...
;         for (int ck = 0; ck < 8; ++ck) {
; #pragma unroll
;             for (int it = 0; it < 4; ++it) { const int n = lane + 64 * it; *(LAS u32x4*)(hst + (n >> 4) * IMG_PITCH + (n & 15) * 16) = hv[it]; }
;             if (ck + 1 < 8) {
; #pragma unroll
;                 for (int it = 0; it < 4; ++it) { const int n = lane + 64 * it; hv[it] = __builtin_nontemporal_load((const u32x4*)(hrow + (size_t)(n >> 4) * 1024 + (ck + 1) * 128 + (n & 15) * 8)); } }
; #pragma unroll
;             for (int ks = 0; ks < 4; ++ks) {
;                 const bf16x8 af = *(const LAS bf16x8*)(hst + r * IMG_PITCH + 64 * ks + 16 * g);
;                 bf16x8 bfw = {0, 0, 0, 0, 0, 0, 0, 0};
;                 if (r < 8) bfw = *(const LAS bf16x8*)(wl + r * 2064 + (ck * 128 + 32 * ks + 8 * g) * 2);
;                 dacc = MFMA16(af, bfw, dacc);
;             }
;             asm volatile("" ::: "memory");
;         }
	v_mfma_f32_16x16x32_bf16 v[20:23], v[24:27], v[92:95], v[20:23]
	v_mfma_f32_16x16x32_bf16 v[20:23], v[28:31], v[96:99], v[20:23]
	ds_read_b128 v[24:27], v245 offset:128
	ds_read_b128 v[28:31], v245 offset:192
	s_and_saveexec_b64 s[60:61], s[38:39]
	ds_read_b128 v[92:95], v246 offset:896
	ds_read_b128 v[96:99], v246 offset:960
	s_or_b64 exec, exec, s[60:61]
	s_waitcnt lgkmcnt(0)
	v_mfma_f32_16x16x32_bf16 v[20:23], v[24:27], v[92:95], v[20:23]
	v_mfma_f32_16x16x32_bf16 v[20:23], v[28:31], v[96:99], v[20:23]
	s_waitcnt vmcnt(12)
	ds_write_b128 v244, v[4:7]
	ds_write_b128 v244, v[8:11] offset:1088
	ds_write_b128 v244, v[12:15] offset:2176
	ds_write_b128 v244, v[16:19] offset:3264
	ds_read_b128 v[24:27], v245
	ds_read_b128 v[28:31], v245 offset:64
	s_and_saveexec_b64 s[60:61], s[38:39]
	ds_read_b128 v[92:95], v246 offset:1024
	ds_read_b128 v[96:99], v246 offset:1088
	s_or_b64 exec, exec, s[60:61]
	s_waitcnt lgkmcnt(0)
	v_mfma_f32_16x16x32_bf16 v[20:23], v[24:27], v[92:95], v[20:23]
	v_mfma_f32_16x16x32_bf16 v[20:23], v[28:31], v[96:99], v[20:23]
	ds_read_b128 v[24:27], v245 offset:128
	ds_read_b128 v[28:31], v245 offset:192
	s_and_saveexec_b64 s[60:61], s[38:39]
	ds_read_b128 v[92:95], v246 offset:1152
	ds_read_b128 v[96:99], v246 offset:1216
	s_or_b64 exec, exec, s[60:61]
	s_waitcnt lgkmcnt(0)
	v_mfma_f32_16x16x32_bf16 v[20:23], v[24:27], v[92:95], v[20:23]
	v_mfma_f32_16x16x32_bf16 v[20:23], v[28:31], v[96:99], v[20:23]
	s_waitcnt vmcnt(8)
	ds_write_b128 v244, v[38:41]
	ds_write_b128 v244, v[42:45] offset:1088
	ds_write_b128 v244, v[46:49] offset:2176
	ds_write_b128 v244, v[50:53] offset:3264
	ds_read_b128 v[24:27], v245
	ds_read_b128 v[28:31], v245 offset:64
	s_and_saveexec_b64 s[60:61], s[38:39]
	ds_read_b128 v[92:95], v246 offset:1280
	ds_read_b128 v[96:99], v246 offset:1344
	s_or_b64 exec, exec, s[60:61]
	s_waitcnt lgkmcnt(0)
	v_mfma_f32_16x16x32_bf16 v[20:23], v[24:27], v[92:95], v[20:23]
	v_mfma_f32_16x16x32_bf16 v[20:23], v[28:31], v[96:99], v[20:23]
	ds_read_b128 v[24:27], v245 offset:128
	ds_read_b128 v[28:31], v245 offset:192
	s_and_saveexec_b64 s[60:61], s[38:39]
	ds_read_b128 v[92:95], v246 offset:1408
	ds_read_b128 v[96:99], v246 offset:1472
	s_or_b64 exec, exec, s[60:61]
	s_waitcnt lgkmcnt(0)
	v_mfma_f32_16x16x32_bf16 v[20:23], v[24:27], v[92:95], v[20:23]
	v_mfma_f32_16x16x32_bf16 v[20:23], v[28:31], v[96:99], v[20:23]
	s_waitcnt vmcnt(4)
	ds_write_b128 v244, v[54:57]
	ds_write_b128 v244, v[58:61] offset:1088
	ds_write_b128 v244, v[62:65] offset:2176
	ds_write_b128 v244, v[66:69] offset:3264
	ds_read_b128 v[24:27], v245
	ds_read_b128 v[28:31], v245 offset:64
	s_and_saveexec_b64 s[60:61], s[38:39]
	ds_read_b128 v[92:95], v246 offset:1536
	ds_read_b128 v[96:99], v246 offset:1600
	s_or_b64 exec, exec, s[60:61]
	s_waitcnt lgkmcnt(0)
	v_mfma_f32_16x16x32_bf16 v[20:23], v[24:27], v[92:95], v[20:23]
	v_mfma_f32_16x16x32_bf16 v[20:23], v[28:31], v[96:99], v[20:23]
	ds_read_b128 v[24:27], v245 offset:128
	ds_read_b128 v[28:31], v245 offset:192
	s_and_saveexec_b64 s[60:61], s[38:39]
	ds_read_b128 v[92:95], v246 offset:1664
	ds_read_b128 v[96:99], v246 offset:1728
	s_or_b64 exec, exec, s[60:61]
	s_waitcnt lgkmcnt(0)
	v_mfma_f32_16x16x32_bf16 v[20:23], v[24:27], v[92:95], v[20:23]
	v_mfma_f32_16x16x32_bf16 v[20:23], v[28:31], v[96:99], v[20:23]
	s_waitcnt vmcnt(0)
	ds_write_b128 v244, v[70:73]
	ds_write_b128 v244, v[74:77] offset:1088
	ds_write_b128 v244, v[78:81] offset:2176
	ds_write_b128 v244, v[82:85] offset:3264
	ds_read_b128 v[24:27], v245
	ds_read_b128 v[28:31], v245 offset:64
	s_and_saveexec_b64 s[60:61], s[38:39]
	ds_read_b128 v[92:95], v246 offset:1792
	ds_read_b128 v[96:99], v246 offset:1856
	s_or_b64 exec, exec, s[60:61]
	s_waitcnt lgkmcnt(0)
	v_mfma_f32_16x16x32_bf16 v[20:23], v[24:27], v[92:95], v[20:23]
	v_mfma_f32_16x16x32_bf16 v[20:23], v[28:31], v[96:99], v[20:23]
	ds_read_b128 v[24:27], v245 offset:128
	ds_read_b128 v[28:31], v245 offset:192
	s_and_saveexec_b64 s[60:61], s[38:39]
	ds_read_b128 v[92:95], v246 offset:1920
	ds_read_b128 v[96:99], v246 offset:1984
	s_or_b64 exec, exec, s[60:61]
	s_waitcnt lgkmcnt(0)
	v_mfma_f32_16x16x32_bf16 v[20:23], v[24:27], v[92:95], v[20:23]
	v_mfma_f32_16x16x32_bf16 v[4:7], v[28:31], v[96:99], v[20:23]
	s_and_saveexec_b64 s[60:61], s[38:39]
	s_cbranch_execz .LBB0_343
; DI void ssd_part1_unit(int u, const bf16* PROJ, float* DT, const bf16* H, const bf16* wdtb_l, const float* dt_bias_l, const float* cw, const float* cb, const float* a_log_l, float* STATES, float* TOT,
;                        LAS unsigned char* ldsu, int tid, int wave, int lane) {
;     ...
;         if (r < 8) { const float bias = dt_bias_l[r];
; #pragma unroll
;             for (int i = 0; i < 4; ++i) { const float xx = dacc[i] + bias; DT[(size_t)(b * T + t0 + 16 * wave + 4 * g + i) * 8 + r] = xx > 20.f ? xx : log1pf(__expf(xx)); } }
	s_nop 0
	global_load_dword v10, v[106:107], off
	s_mov_b32 s1, 0x41a00000
	s_waitcnt vmcnt(0)
	s_nop 1
	v_add_f32_e32 v4, v4, v10
	v_cmp_nlt_f32_e32 vcc, s1, v4
	s_and_saveexec_b64 s[64:65], vcc
	s_cbranch_execz .LBB0_336
	v_mul_f32_e32 v4, 0x3fb8aa3b, v4
	v_exp_f32_e32 v4, v4
	s_mov_b32 s1, 0x3f2aaaab
	v_add_f32_e32 v11, 1.0, v4
	v_frexp_mant_f32_e32 v13, v11
	v_cvt_f64_f32_e32 v[8:9], v11
	v_frexp_exp_i32_f64_e32 v8, v[8:9]
	v_cmp_gt_f32_e32 vcc, s1, v13
	v_add_f32_e32 v12, -1.0, v11
	v_sub_f32_e32 v14, v12, v11
	v_subbrev_co_u32_e32 v18, vcc, 0, v8, vcc
	v_sub_u32_e32 v8, 0, v18
	v_sub_f32_e32 v12, v4, v12
	v_add_f32_e32 v14, 1.0, v14
	v_ldexp_f32 v9, v11, v8
	v_add_f32_e32 v12, v12, v14
	v_add_f32_e32 v11, -1.0, v9
	v_add_f32_e32 v13, 1.0, v9
	v_ldexp_f32 v8, v12, v8
	v_add_f32_e32 v12, 1.0, v11
	v_add_f32_e32 v14, -1.0, v13
	v_sub_f32_e32 v12, v9, v12
	v_sub_f32_e32 v9, v9, v14
	v_add_f32_e32 v12, v8, v12
	v_add_f32_e32 v8, v8, v9
	v_add_f32_e32 v19, v13, v8
	v_rcp_f32_e32 v21, v19
	v_sub_f32_e32 v9, v19, v13
	v_sub_f32_e32 v20, v8, v9
	v_add_f32_e32 v9, v11, v12
	v_sub_f32_e32 v8, v9, v11
	v_mul_f32_e32 v22, v9, v21
	v_sub_f32_e32 v11, v12, v8
	v_mul_f32_e32 v12, v19, v22
	v_fma_f32 v14, v22, v19, -v12
	v_fmac_f32_e32 v14, v22, v20
	v_add_f32_e32 v8, v12, v14
	v_sub_f32_e32 v13, v9, v8
	v_pk_add_f32 v[16:17], v[8:9], v[12:13] neg_lo:[0,1] neg_hi:[0,1]
	v_mov_b32_e32 v15, v8
	v_pk_add_f32 v[8:9], v[16:17], v[14:15] neg_lo:[0,1] neg_hi:[0,1]
	s_mov_b32 s1, 0x3f317218
	v_add_f32_e32 v9, v11, v9
	v_add_f32_e32 v8, v8, v9
	v_add_f32_e32 v9, v13, v8
	v_mul_f32_e32 v11, v21, v9
	v_mul_f32_e32 v12, v19, v11
	v_fma_f32 v14, v11, v19, -v12
	v_fmac_f32_e32 v14, v11, v20
	v_sub_f32_e32 v13, v13, v9
	v_add_f32_e32 v19, v8, v13
	v_add_f32_e32 v8, v12, v14
	v_sub_f32_e32 v13, v9, v8
	v_pk_add_f32 v[16:17], v[8:9], v[12:13] neg_lo:[0,1] neg_hi:[0,1]
	v_mov_b32_e32 v15, v8
	v_pk_add_f32 v[8:9], v[16:17], v[14:15] neg_lo:[0,1] neg_hi:[0,1]
	s_nop 0
	v_add_f32_e32 v9, v19, v9
	v_add_f32_e32 v8, v8, v9
	v_add_f32_e32 v9, v22, v11
	v_add_f32_e32 v8, v13, v8
	v_sub_f32_e32 v12, v9, v22
	v_mul_f32_e32 v8, v21, v8
	v_sub_f32_e32 v11, v11, v12
	v_add_f32_e32 v11, v11, v8
	v_add_f32_e32 v12, v9, v11
	v_mul_f32_e32 v14, v12, v12
	v_mov_b32_e32 v8, 0x3ecc95a3
	v_fmamk_f32 v8, v14, 0x3e9b6dac, v8
	v_fmaak_f32 v193, v14, v8, 0x3f2aaada
	v_cvt_f32_i32_e32 v8, v18
	v_sub_f32_e32 v9, v12, v9
	v_sub_f32_e32 v9, v11, v9
	v_ldexp_f32 v11, v9, 1
	v_mul_f32_e32 v9, v12, v14
	v_pk_mul_f32 v[14:15], v[8:9], v[192:193]
	v_ldexp_f32 v13, v12, 1
	v_fma_f32 v12, v8, s1, -v14
	v_fmac_f32_e32 v12, 0xb102e308, v8
	v_pk_add_f32 v[8:9], v[14:15], v[12:13]
	v_mov_b32_e32 v16, v14
	v_sub_f32_e32 v13, v9, v13
	v_sub_f32_e32 v13, v15, v13
	v_add_f32_e32 v17, v11, v13
	v_pk_add_f32 v[14:15], v[8:9], v[14:15] neg_lo:[0,1] neg_hi:[0,1]
	v_pk_add_f32 v[18:19], v[8:9], v[16:17]
	v_mov_b32_e32 v13, v8
	v_mov_b32_e32 v15, v19
	v_pk_add_f32 v[20:21], v[12:13], v[14:15] neg_lo:[0,1] neg_hi:[0,1]
	v_pk_add_f32 v[12:13], v[12:13], v[14:15]
	v_mov_b32_e32 v16, v17
	v_pk_add_f32 v[14:15], v[12:13], v[8:9] op_sel:[1,0] op_sel_hi:[0,1] neg_lo:[0,1] neg_hi:[0,1]
	v_pk_add_f32 v[22:23], v[18:19], v[14:15] op_sel_hi:[1,0] neg_lo:[0,1] neg_hi:[0,1]
	v_mov_b32_e32 v18, v19
	v_mov_b32_e32 v19, v13
	v_pk_mov_b32 v[14:15], v[8:9], v[14:15] op_sel:[1,0]
	v_mov_b32_e32 v17, v8
	v_pk_add_f32 v[14:15], v[18:19], v[14:15] neg_lo:[0,1] neg_hi:[0,1]
	v_mov_b32_e32 v22, v20
	v_pk_add_f32 v[8:9], v[16:17], v[14:15] neg_lo:[0,1] neg_hi:[0,1]
	v_mov_b32_e32 v21, v13
	v_pk_add_f32 v[14:15], v[22:23], v[8:9]
	s_mov_b32 s1, 0x7f800000
	v_pk_add_f32 v[16:17], v[14:15], v[14:15] op_sel:[0,1] op_sel_hi:[1,0]
	v_cmp_neq_f32_e32 vcc, s1, v4
	v_pk_add_f32 v[12:13], v[12:13], v[16:17] op_sel:[1,0] op_sel_hi:[0,1]
	v_mov_b32_e32 v15, v12
	v_pk_add_f32 v[18:19], v[14:15], v[20:21] neg_lo:[0,1] neg_hi:[0,1]
	v_mov_b32_e32 v9, v16
	v_sub_f32_e32 v11, v14, v18
	v_pk_add_f32 v[8:9], v[8:9], v[18:19] neg_lo:[0,1] neg_hi:[0,1]
	v_sub_f32_e32 v11, v20, v11
	v_add_f32_e32 v8, v8, v11
	v_add_f32_e32 v8, v8, v9
	v_add_f32_e32 v8, v12, v8
	v_mov_b32_e32 v9, 0x7f800000
	v_cndmask_b32_e32 v8, v9, v8, vcc
	v_cmp_ngt_f32_e32 vcc, -1.0, v4
	v_mov_b32_e32 v9, 0x7fc00000
	s_mov_b32 s1, 0x33800000
	v_cndmask_b32_e32 v8, v9, v8, vcc
	v_cmp_neq_f32_e32 vcc, -1.0, v4
	v_mov_b32_e32 v9, 0xff800000
	s_nop 0
	v_cndmask_b32_e32 v8, v9, v8, vcc
	v_cmp_lt_f32_e64 vcc, |v4|, s1
	s_nop 1
	v_cndmask_b32_e32 v4, v8, v4, vcc
